# P3a prep loop software-pipelined (row + rope prefetch), static s_setprio 1 for waves 4-7 inside MLA flash items
# speedup vs baseline: 1.0747x; 1.0029x over previous
; #define PIN(i) ((const float*)(const GASP float*)karg_q(i))
; __device__ __forceinline__ int obid() { int b = blockIdx.x; asm volatile("" : "+s"(b)); return b; }
; __device__ __forceinline__ int otid() { int t = threadIdx.x; asm volatile("" : "+v"(t)); return t; }
; __device__ __forceinline__ void p3_prep(const Params& P, int l) {
;     const int tid = otid(), lane = tid & 63, wave = tid >> 6;
;     bf16_t* U = (bf16_t*)(PWS + WS_U);
;     bf16_t* MK = (bf16_t*)(PWS + WS_MK); bf16_t* A2 = (bf16_t*)(PWS + WS_A2);
;     const float* rope = (const float*)(PWS + WS_ROPE);
;     const int sub = lane & 7;
;     float gA[8], gB[8], gC[8];
;     { const float* nqg = PIN(9) + l * 64 + sub * 8; const float* nkg = PIN(10) + l * 64 + sub * 8;
; #pragma unroll
;       for (int j = 0; j < 8; ++j) { gA[j] = lane < 48 ? nqg[j] * NA_QSCALE : nkg[j]; gB[j] = nkg[j]; }
;       const float* gc = lane < 32 ? PIN(12) + l * 256 + lane * 8 : (lane < 48 ? PIN(14) + l * 128 + (lane - 32) * 8 : PIN(17) + l * 96 + 64 + ((lane - 48) & 3) * 8);
; #pragma unroll
;       for (int j = 0; j < 8; ++j) gC[j] = gc[j]; }
;     for (int row = obid() * 8 + wave; row < MTOK; row += gridDim.x * 8) {
;         bf16_t* u = U + (size_t)row * NINP;
;         const bool latent = row < NLAT;
;         const uint4 ra = *(const uint4*)(u + lane * 8);
;         const uint4 rb = *(const uint4*)(u + 512 + (lane & 31) * 8);
;         const uint4 rc = *(const uint4*)(u + OCQ + (lane < 52 ? lane : 51) * 8);
.LBB0_575:
	s_or_b64 exec, exec, s[2:3]
	global_load_dwordx4 v[2:5], v[6:7], off offset:16
	s_nop 0
	global_load_dwordx4 v[6:9], v[6:7], off
	v_ashrrev_i32_e32 v1, 6, v10
	s_mov_b32 s2, s63
	s_nop 0
	v_lshl_add_u32 v1, s2, 3, v1
	v_cmp_gt_i32_e32 vcc, s10, v1
	s_and_saveexec_b64 s[2:3], vcc
	s_cbranch_execz .LBB0_592
	v_min_u32_e32 v13, 51, v11
	v_and_b32_e32 v10, 1, v10
	v_readlane_b32 s6, v255, 9
	v_lshlrev_b32_e32 v34, 3, v11
	v_and_b32_e32 v12, 0xf8, v12
	v_cmp_gt_u32_e64 s[46:47], 52, v11
	v_lshlrev_b32_e32 v38, 3, v13
	v_cmp_gt_u32_e64 s[48:49], 50, v11
	v_cmp_eq_u32_e64 s[50:51], 0, v10
	v_lshlrev_b32_e32 v10, 4, v11
	v_mov_b32_e32 v11, v0
	v_readlane_b32 s7, v255, 10
	v_lshl_add_u64 v[30:31], s[56:57], 0, v[10:11]
	s_mov_b64 s[16:17], 0
	v_lshl_add_u64 v[32:33], s[6:7], 0, v[10:11]
	v_lshlrev_b32_e32 v34, 1, v34
	v_lshlrev_b32_e32 v36, 1, v12
	v_lshlrev_b32_e32 v38, 1, v38
	v_mul_lo_u32 v92, v1, s90
	v_add_u32_e32 v93, v92, v34
	global_load_dwordx4 v[80:83], v93, s[68:69]
	v_add_u32_e32 v93, v92, v36
	global_load_dwordx4 v[84:87], v93, s[68:69] offset:1024
	v_add_u32_e32 v93, v92, v38
	global_load_dwordx4 v[88:91], v93, s[68:69] offset:2304
	s_waitcnt vmcnt(0)
	s_branch .Lprep_entry

; template <int K> __device__ __forceinline__ float swz(float v) { return __int_as_float(__builtin_amdgcn_ds_swizzle(__float_as_int(v), (K << 10) | 0x1f)); }
; __device__ __forceinline__ int obid() { int b = blockIdx.x; asm volatile("" : "+s"(b)); return b; }
; __device__ __forceinline__ void unpack8(const uint4 r, float (&v)[8]) { v[0] = bflo(r.x); v[1] = bfhi(r.x); v[2] = bflo(r.y); v[3] = bfhi(r.y); v[4] = bflo(r.z); v[5] = bfhi(r.z); v[6] = bflo(r.w); v[7] = bfhi(r.w); }
; __device__ __forceinline__ uint4 pack8(const float (&v)[8]) { uint4 w; w.x = pk2(v[0], v[1]); w.y = pk2(v[2], v[3]); w.z = pk2(v[4], v[5]); w.w = pk2(v[6], v[7]); return w; }
; __device__ __forceinline__ void p3_prep(const Params& P, int l) {
;     ...
;     for (int row = obid() * 8 + wave; row < MTOK; row += gridDim.x * 8) {
;         bf16_t* u = U + (size_t)row * NINP;
;         const bool latent = row < NLAT;
;         const uint4 ra = *(const uint4*)(u + lane * 8);
;         const uint4 rb = *(const uint4*)(u + 512 + (lane & 31) * 8);
;         const uint4 rc = *(const uint4*)(u + OCQ + (lane < 52 ? lane : 51) * 8);
;         float v[8];
;         unpack8(ra, v);
;         { float s = 0.f;
; #pragma unroll
;           for (int j = 0; j < 8; ++j) s += v[j] * v[j];
;           s += swz<1>(s); s += swz<2>(s); s += swz<4>(s);
;           const float rs = rsqrtf(s * (1.0f / 64.0f) + EPS);
; #pragma unroll
;           for (int j = 0; j < 8; ++j) v[j] = v[j] * rs * gA[j];
;           *(uint4*)(u + lane * 8) = pack8(v); }
;         unpack8(rb, v);
;         { float s = 0.f;
; #pragma unroll
;           for (int j = 0; j < 8; ++j) s += v[j] * v[j];
;           s += swz<1>(s); s += swz<2>(s); s += swz<4>(s);
;           const float rs = rsqrtf(s * (1.0f / 64.0f) + EPS);
; #pragma unroll
;           for (int j = 0; j < 8; ++j) v[j] = v[j] * rs * gB[j];
;           if (lane < 32) *(uint4*)(u + 512 + lane * 8) = pack8(v); }
.LBB0_578:
	s_waitcnt vmcnt(9)
.Lprep_entry:
	v_mov_b64_e32 v[10:11], s[68:69]
	v_mad_i64_i32 v[10:11], s[6:7], v1, s90, v[10:11]
	s_waitcnt lgkmcnt(8)
	v_mov_b32_e32 v35, v0
	v_lshl_add_u64 v[40:41], v[10:11], 0, v[34:35]
	s_waitcnt lgkmcnt(0)
	v_mov_b32_e32 v37, v0
	v_lshl_add_u64 v[12:13], v[10:11], 0, v[36:37]
	v_mov_b32_e32 v39, v0
	v_lshl_add_u64 v[10:11], v[10:11], 0, v[38:39]
	s_mov_b64 s[98:99], 0x900000
	v_lshl_add_u64 v[92:93], v[40:41], 0, s[98:99]
	v_lshl_add_u64 v[94:95], v[12:13], 0, s[98:99]
	v_lshl_add_u64 v[96:97], v[10:11], 0, s[98:99]
	v_bfe_u32 v98, v1, 6, 5
	v_and_b32_e32 v99, 63, v1
	v_cndmask_b32_e64 v98, v99, v98, s[48:49]
	v_lshlrev_b32_e32 v98, 6, v98
	global_load_dwordx4 v[100:103], v98, s[22:23] offset:48
	global_load_dwordx4 v[104:107], v98, s[22:23] offset:32
	global_load_dwordx4 v[108:111], v98, s[22:23] offset:16
	global_load_dwordx4 v[112:115], v98, s[22:23]
	v_mov_b32_e32 v42, v80
	v_mov_b32_e32 v43, v81
	v_mov_b32_e32 v44, v82
	v_mov_b32_e32 v45, v83
	v_mov_b32_e32 v50, v84
	v_mov_b32_e32 v51, v85
	v_mov_b32_e32 v52, v86
	v_mov_b32_e32 v53, v87
	v_mov_b32_e32 v10, v88
	v_mov_b32_e32 v11, v89
	v_mov_b32_e32 v12, v90
	v_mov_b32_e32 v13, v91
	global_load_dwordx4 v[80:83], v[92:93], off
	global_load_dwordx4 v[84:87], v[94:95], off offset:1024
	global_load_dwordx4 v[88:91], v[96:97], off offset:2304
	v_lshlrev_b32_e32 v46, 16, v42
	v_and_b32_e32 v47, 0xffff0000, v42
	v_lshlrev_b32_e32 v42, 16, v43
	v_and_b32_e32 v43, 0xffff0000, v43
	v_pk_mul_f32 v[60:61], v[46:47], v[46:47]
	v_pk_mul_f32 v[58:59], v[42:43], v[42:43]
	v_add_f32_e32 v35, v60, v61
	v_lshlrev_b32_e32 v48, 16, v44
	v_and_b32_e32 v49, 0xffff0000, v44
	v_add_f32_e32 v35, v35, v58
	v_pk_mul_f32 v[56:57], v[48:49], v[48:49]
	v_add_f32_e32 v35, v59, v35
	v_lshlrev_b32_e32 v44, 16, v45
	v_and_b32_e32 v45, 0xffff0000, v45
	v_add_f32_e32 v35, v56, v35
	v_pk_mul_f32 v[54:55], v[44:45], v[44:45]
	v_add_f32_e32 v35, v57, v35
	v_add_f32_e32 v35, v54, v35
	v_add_f32_e32 v35, v55, v35
	ds_swizzle_b32 v37, v35 offset:swizzle(SWAP,1)
	s_waitcnt lgkmcnt(0)
	v_add_f32_e32 v35, v35, v37
	ds_swizzle_b32 v37, v35 offset:swizzle(SWAP,2)
	s_waitcnt lgkmcnt(0)
	v_add_f32_e32 v35, v35, v37
	ds_swizzle_b32 v37, v35 offset:swizzle(SWAP,4)
	s_waitcnt lgkmcnt(0)
	v_add_f32_e32 v35, v35, v37
	v_mov_b32_e32 v37, 0x358637bd
	v_fmamk_f32 v35, v35, 0x3c800000, v37
	v_cmp_gt_f32_e32 vcc, s88, v35
	v_mul_f32_e32 v37, 0x4b800000, v35
	s_nop 0
	v_cndmask_b32_e32 v35, v35, v37, vcc
	v_rsq_f32_e32 v35, v35
	s_nop 0
	v_mul_f32_e32 v37, 0x45800000, v35
	v_cndmask_b32_e32 v54, v35, v37, vcc
	v_pk_mul_f32 v[42:43], v[54:55], v[42:43] op_sel_hi:[0,1]
	v_pk_mul_f32 v[56:57], v[20:21], v[42:43]
	v_pk_mul_f32 v[42:43], v[54:55], v[48:49] op_sel_hi:[0,1]
	v_pk_mul_f32 v[46:47], v[54:55], v[46:47] op_sel_hi:[0,1]
	v_pk_mul_f32 v[48:49], v[24:25], v[42:43]
	v_pk_mul_f32 v[42:43], v[54:55], v[44:45] op_sel_hi:[0,1]
	v_pk_mul_f32 v[46:47], v[16:17], v[46:47]
	v_pk_mul_f32 v[54:55], v[28:29], v[42:43]
	v_cvt_pk_bf16_f32 v44, v48, v49
	s_nop 0
	v_lshlrev_b32_e32 v48, 16, v50
	v_and_b32_e32 v49, 0xffff0000, v50
	v_cvt_pk_bf16_f32 v42, v46, v47
	v_cvt_pk_bf16_f32 v43, v56, v57
	v_cvt_pk_bf16_f32 v45, v54, v55
	v_lshlrev_b32_e32 v46, 16, v51
	v_and_b32_e32 v47, 0xffff0000, v51
	v_pk_mul_f32 v[50:51], v[48:49], v[48:49]
	global_store_dwordx4 v[40:41], v[42:45], off
	v_add_f32_e32 v35, v50, v51
	s_nop 0
	v_lshlrev_b32_e32 v44, 16, v52
	v_and_b32_e32 v45, 0xffff0000, v52
	v_lshlrev_b32_e32 v42, 16, v53
	v_and_b32_e32 v43, 0xffff0000, v53
	v_pk_mul_f32 v[52:53], v[46:47], v[46:47]
	v_pk_mul_f32 v[54:55], v[44:45], v[44:45]
	v_add_f32_e32 v35, v35, v52
	v_add_f32_e32 v35, v53, v35
	v_add_f32_e32 v35, v54, v35
	v_pk_mul_f32 v[56:57], v[42:43], v[42:43]
	v_add_f32_e32 v35, v55, v35
	v_add_f32_e32 v35, v56, v35
	v_add_f32_e32 v35, v57, v35
	ds_swizzle_b32 v37, v35 offset:swizzle(SWAP,1)
	s_waitcnt lgkmcnt(0)
	v_add_f32_e32 v35, v35, v37
	ds_swizzle_b32 v37, v35 offset:swizzle(SWAP,2)
	s_waitcnt lgkmcnt(0)
	v_add_f32_e32 v35, v35, v37
	ds_swizzle_b32 v37, v35 offset:swizzle(SWAP,4)
	s_and_saveexec_b64 s[20:21], s[42:43]
	s_cbranch_execz .LBB0_580
	s_waitcnt lgkmcnt(0)
	v_add_f32_e32 v35, v35, v37
	v_mov_b32_e32 v37, 0x358637bd
	v_fmamk_f32 v35, v35, 0x3c800000, v37
	v_mul_f32_e32 v37, 0x4b800000, v35
	v_cmp_gt_f32_e32 vcc, s88, v35
	s_nop 1
	v_cndmask_b32_e32 v35, v35, v37, vcc
	v_rsq_f32_e32 v35, v35
	s_nop 0
	v_mul_f32_e32 v37, 0x45800000, v35
	v_cndmask_b32_e32 v50, v35, v37, vcc
	v_pk_mul_f32 v[48:49], v[50:51], v[48:49] op_sel_hi:[0,1]
	v_pk_mul_f32 v[46:47], v[50:51], v[46:47] op_sel_hi:[0,1]
	v_pk_mul_f32 v[44:45], v[50:51], v[44:45] op_sel_hi:[0,1]
	v_pk_mul_f32 v[42:43], v[50:51], v[42:43] op_sel_hi:[0,1]
	v_pk_mul_f32 v[48:49], v[14:15], v[48:49]
	v_pk_mul_f32 v[46:47], v[18:19], v[46:47]
	v_pk_mul_f32 v[44:45], v[22:23], v[44:45]
	v_pk_mul_f32 v[50:51], v[26:27], v[42:43]
	v_cvt_pk_bf16_f32 v42, v48, v49
	v_cvt_pk_bf16_f32 v43, v46, v47
	v_cvt_pk_bf16_f32 v44, v44, v45
	v_cvt_pk_bf16_f32 v45, v50, v51
	global_store_dwordx4 v[40:41], v[42:45], off offset:1024
; template <int K> __device__ __forceinline__ float swz(float v) { return __int_as_float(__builtin_amdgcn_ds_swizzle(__float_as_int(v), (K << 10) | 0x1f)); }
; __device__ __forceinline__ void unpack8(const uint4 r, float (&v)[8]) { v[0] = bflo(r.x); v[1] = bfhi(r.x); v[2] = bflo(r.y); v[3] = bfhi(r.y); v[4] = bflo(r.z); v[5] = bfhi(r.z); v[6] = bflo(r.w); v[7] = bfhi(r.w); }
; __device__ __forceinline__ uint4 pack8(const float (&v)[8]) { uint4 w; w.x = pk2(v[0], v[1]); w.y = pk2(v[2], v[3]); w.z = pk2(v[4], v[5]); w.w = pk2(v[6], v[7]); return w; }
; __device__ __forceinline__ void p3_prep(const Params& P, int l) {
;     ...
;         unpack8(rc, v);
;         { float s = 0.f;
; #pragma unroll
;           for (int j = 0; j < 8; ++j) s += v[j] * v[j];
;           s += swz<1>(s); const float s2 = s + swz<2>(s); const float s3 = s2 + swz<4>(s2); const float s4 = s3 + swz<8>(s3); const float s5 = s4 + swz<16>(s4);
;           const float ms = lane < 32 ? s5 * (1.0f / 256.0f) : (lane < 48 ? s4 * (1.0f / 128.0f) : s2 * (1.0f / 32.0f));
;           const float rs = rsqrtf(ms + EPS);
; #pragma unroll
;           for (int j = 0; j < 8; ++j) v[j] = v[j] * rs * gC[j];
;           float pv[8];
; #pragma unroll
;           for (int j = 0; j < 8; ++j) pv[j] = swz<1>(v[j]);
;           if (lane < 48) { *(uint4*)(A2 + (size_t)row * 384 + lane * 8) = pack8(v); }
;           else if (lane < 52) {
;               const int q4 = lane - 48;
;               if (latent) {
;                   const int pos = row & 2047, pp = (q4 < 2) ? (pos >> 6) : (pos & 63);
;                   const float* rt = rope + pp * 16;
; #pragma unroll
;                   for (int j = 0; j < 8; ++j) { const float c = rt[2 * j], sn = rt[2 * j + 1];
;                       v[j] = (q4 & 1) ? pv[j] * sn + v[j] * c : v[j] * c - pv[j] * sn; }
.LBB0_580:
	s_or_b64 exec, exec, s[20:21]
	s_nop 0
	v_lshlrev_b32_e32 v44, 16, v10
	v_and_b32_e32 v45, 0xffff0000, v10
	v_lshlrev_b32_e32 v10, 16, v11
	v_and_b32_e32 v11, 0xffff0000, v11
	v_lshlrev_b32_e32 v40, 16, v12
	v_and_b32_e32 v41, 0xffff0000, v12
	v_lshlrev_b32_e32 v42, 16, v13
	v_and_b32_e32 v43, 0xffff0000, v13
	v_pk_mul_f32 v[12:13], v[44:45], v[44:45]
	v_pk_mul_f32 v[46:47], v[10:11], v[10:11]
	v_add_f32_e32 v12, v12, v13
	v_add_f32_e32 v12, v12, v46
	v_pk_mul_f32 v[48:49], v[40:41], v[40:41]
	v_add_f32_e32 v12, v47, v12
	v_add_f32_e32 v12, v48, v12
	v_pk_mul_f32 v[50:51], v[42:43], v[42:43]
	v_add_f32_e32 v12, v49, v12
	v_add_f32_e32 v12, v50, v12
	v_add_f32_e32 v12, v51, v12
	ds_swizzle_b32 v13, v12 offset:swizzle(SWAP,1)
	s_waitcnt lgkmcnt(0)
	v_add_f32_e32 v12, v12, v13
	ds_swizzle_b32 v13, v12 offset:swizzle(SWAP,2)
	s_waitcnt lgkmcnt(0)
	v_add_f32_e32 v37, v12, v13
	ds_swizzle_b32 v12, v37 offset:swizzle(SWAP,4)
	s_waitcnt lgkmcnt(0)
	v_add_f32_e32 v12, v37, v12
	ds_swizzle_b32 v13, v12 offset:swizzle(SWAP,8)
	s_waitcnt lgkmcnt(0)
	v_add_f32_e32 v13, v12, v13
	ds_swizzle_b32 v35, v13 offset:swizzle(SWAP,16)
	s_and_saveexec_b64 s[6:7], s[44:45]
	s_xor_b64 s[20:21], exec, s[6:7]
	v_mul_f32_e32 v12, 0x3c000000, v13
	v_mul_f32_e32 v13, 0x3d000000, v37
	v_cndmask_b32_e64 v12, v13, v12, s[38:39]
	s_andn2_saveexec_b64 s[20:21], s[20:21]
	s_cbranch_execz .LBB0_584
	s_waitcnt lgkmcnt(0)
	v_add_f32_e32 v12, v13, v35
	v_mul_f32_e32 v12, 0x3b800000, v12
.LBB0_584:
	s_or_b64 exec, exec, s[20:21]
	v_add_f32_e32 v12, 0x358637bd, v12
	v_mul_f32_e32 v13, 0x4b800000, v12
	v_cmp_gt_f32_e32 vcc, s88, v12
	s_nop 1
	v_cndmask_b32_e32 v12, v12, v13, vcc
	v_rsq_f32_e32 v12, v12
	s_nop 0
	v_mul_f32_e32 v13, 0x45800000, v12
	v_cndmask_b32_e32 v46, v12, v13, vcc
	v_pk_mul_f32 v[12:13], v[46:47], v[44:45] op_sel_hi:[0,1]
	v_pk_mul_f32 v[44:45], v[46:47], v[10:11] op_sel_hi:[0,1]
	v_pk_mul_f32 v[40:41], v[46:47], v[40:41] op_sel_hi:[0,1]
	v_pk_mul_f32 v[42:43], v[46:47], v[42:43] op_sel_hi:[0,1]
	v_pk_mul_f32 v[10:11], v[6:7], v[12:13]
	v_pk_mul_f32 v[12:13], v[8:9], v[44:45]
	v_pk_mul_f32 v[40:41], v[2:3], v[40:41]
	v_pk_mul_f32 v[42:43], v[4:5], v[42:43]
	ds_swizzle_b32 v50, v10 offset:swizzle(SWAP,1)
	ds_swizzle_b32 v51, v11 offset:swizzle(SWAP,1)
	ds_swizzle_b32 v48, v12 offset:swizzle(SWAP,1)
	ds_swizzle_b32 v49, v13 offset:swizzle(SWAP,1)
	ds_swizzle_b32 v46, v40 offset:swizzle(SWAP,1)
	ds_swizzle_b32 v47, v41 offset:swizzle(SWAP,1)
	ds_swizzle_b32 v44, v42 offset:swizzle(SWAP,1)
	ds_swizzle_b32 v45, v43 offset:swizzle(SWAP,1)
	s_and_saveexec_b64 s[6:7], s[40:41]
	s_xor_b64 s[20:21], exec, s[6:7]
	s_cbranch_execz .LBB0_590
	s_and_saveexec_b64 s[24:25], s[46:47]
	s_cbranch_execz .LBB0_589
	s_mov_b32 s5, 0x8000
	v_cmp_gt_i32_e32 vcc, s5, v1
	s_and_saveexec_b64 s[26:27], vcc
	s_cbranch_execz .LBB0_588
	s_waitcnt lgkmcnt(8)
	s_waitcnt vmcnt(5)
	v_mov_b32_e32 v68, v113
	v_mov_b32_e32 v69, v115
	s_waitcnt lgkmcnt(6)
	v_pk_mul_f32 v[50:51], v[68:69], v[50:51]
	v_mov_b32_e32 v113, v114
	v_cndmask_b32_e64 v51, v51, -v51, s[50:51]
	v_cndmask_b32_e64 v50, v50, -v50, s[50:51]
	v_pk_fma_f32 v[10:11], v[10:11], v[112:113], v[50:51]
	v_mov_b32_e32 v50, v109
	v_mov_b32_e32 v51, v111
	s_waitcnt lgkmcnt(4)
	v_pk_mul_f32 v[48:49], v[50:51], v[48:49]
	v_mov_b32_e32 v109, v110
	v_cndmask_b32_e64 v49, v49, -v49, s[50:51]
	v_cndmask_b32_e64 v48, v48, -v48, s[50:51]
	v_pk_fma_f32 v[12:13], v[12:13], v[108:109], v[48:49]
	v_mov_b32_e32 v48, v105
	v_mov_b32_e32 v49, v107
	s_waitcnt lgkmcnt(2)
	v_pk_mul_f32 v[46:47], v[48:49], v[46:47]
	v_mov_b32_e32 v105, v106
	v_cndmask_b32_e64 v47, v47, -v47, s[50:51]
	v_cndmask_b32_e64 v46, v46, -v46, s[50:51]
	v_pk_fma_f32 v[40:41], v[40:41], v[104:105], v[46:47]
	v_mov_b32_e32 v46, v101
	v_mov_b32_e32 v47, v103
	s_waitcnt lgkmcnt(0)
	v_pk_mul_f32 v[44:45], v[46:47], v[44:45]
	v_mov_b32_e32 v101, v102
	v_cndmask_b32_e64 v45, v45, -v45, s[50:51]
	v_cndmask_b32_e64 v44, v44, -v44, s[50:51]
	v_pk_fma_f32 v[42:43], v[42:43], v[100:101], v[44:45]

; #define PIN(i) ((const float*)(const GASP float*)karg_q(i))
; template <int DQK>
; __device__ __forceinline__ void flash_item(unsigned char* smem, const bf16_t* Q, int qs, const bf16_t* K0, const bf16_t* V0, int n0, const bf16_t* K1, const bf16_t* V1, int n1, int ks, int vs, bf16_t* Oo, int os, float shift) {
;     ...
;     const int tid = otid(), lane = tid & 63, wave = tid >> 6, fr = lane & 15, fq = lane >> 4;
;     LASP unsigned char* ls = (LASP unsigned char*)smem;
;     bf16x8_t qf[2][NKK];
; #pragma unroll
;     for (int qg = 0; qg < 2; ++qg)
; #pragma unroll
; __device__ __forceinline__ void p4_attn(const Params& P, int l, bool last, unsigned char* smem) {
;     ...
;             if (otid() == 0) *slot = __hip_atomic_fetch_add((unsigned*)(PWS + WS_Q) + (size_t)(l * 8 + q) * 64, 1u, __ATOMIC_RELAXED, __HIP_MEMORY_SCOPE_AGENT);
;             __syncthreads();
;             const int i = __builtin_amdgcn_readfirstlane((int)*slot);
;             if (i >= nq) break;
;             unsigned char* ws = PWS;
;             const bf16_t* U = (const bf16_t*)(ws + WS_U);
;             bf16_t* O = (bf16_t*)(ws + WS_AO);
;             if (i >= 96 && i < 192) {
;                 const int j = i - 96, bp = q * 6 + (j >> 4), r = j & 15;
;                 na_item(smem, U, PIN(11) + (size_t)l * 6 * 15 * 31, O, bp / 3, r, bp % 3, shift_nal);
;             } else if (i >= 204) {
;                 const int bh = q * 12 + (i - 204), b = bh / 6, h = bh % 6;
;                 const size_t c0 = (size_t)NLAT + b * CTXL;
;                 flash_item<64>(smem, U + c0 * NINP + OQ + h * 64, NINP, U + c0 * NINP + OKK + h * 64, U + c0 * NINP + OV + h * 64, CTXL, nullptr, nullptr, 0, NINP, NINP, O + c0 * OW + h * 64, OW, shift_nac);
;             } else {
;                 const bf16_t* MQ = (const bf16_t*)(ws + WS_MQ); const bf16_t* MK = (const bf16_t*)(ws + WS_MK); const bf16_t* MV = (const bf16_t*)(ws + WS_MV);
;                 const bool lat = i < 96;
;                 const int bh = q * 12 + (lat ? (i >> 3) : (i - 192)), b = bh / 6, h = bh % 6;
;                 const size_t c0 = (size_t)NLAT + b * CTXL, l0 = (size_t)b * SEQ;
;                 const size_t q0 = lat ? l0 + (i & 7) * 256 : c0;
;                 flash_item<96>(smem, MQ + q0 * 576 + h * 96, 576, MK + c0 * 576 + h * 96, MV + c0 * 384 + h * 64, CTXL, MK + l0 * 576 + h * 96, MV + l0 * 384 + h * 64, lat ? SEQ : 0, 576, 384,
.LBB0_827:
	s_or_b64 exec, exec, s[2:3]
	v_mov_b32_e32 v1, s94
	s_waitcnt lgkmcnt(0)
	s_barrier
	ds_read_b32 v1, v1
	s_mov_b64 s[2:3], -1
	s_waitcnt lgkmcnt(0)
	v_readfirstlane_b32 s13, v1
	s_cmp_ge_i32 s13, s7
	s_cbranch_scc1 .LBB0_822
	s_add_i32 s26, s13, 0xffffffa0
	s_cmpk_gt_u32 s26, 0x5f
	s_cbranch_scc0 .LBB0_838
	s_cmpk_lt_i32 s13, 0xcc
	s_cbranch_scc0 .LBB0_835
	v_readfirstlane_b32 s99, v253
	s_cmp_lt_u32 s99, 0x100
	s_cbranch_scc1 .Lprio_mla_skip
	s_setprio 1
.Lprio_mla_skip:
	s_ashr_i32 s2, s13, 3
	s_add_i32 s3, s13, 0xffffff40
	s_cmpk_lt_i32 s13, 0x60
	s_cselect_b32 s2, s2, s3
	s_cselect_b32 s27, 18, 2
	s_add_i32 s5, s2, s10
	s_mul_hi_i32 s2, s5, 0x2aaaaaab
	s_lshr_b32 s3, s2, 31
	s_add_i32 s2, s2, s3
	s_lshl_b32 s3, s2, 8
	s_ashr_i32 s16, s3, 31
	s_add_u32 s20, s3, 0x8000
	s_addc_u32 s21, s16, 0
	s_ashr_i32 s3, s2, 31
	s_lshl_b64 s[16:17], s[2:3], 11
	s_lshl_b32 s3, s13, 8
	s_and_b32 s3, s3, 0x700
	s_or_b32 s3, s16, s3
	s_cmpk_lt_i32 s13, 0x60
	s_mul_i32 s16, s2, 6
	s_cselect_b32 s28, s17, s21
	s_cselect_b32 s3, s3, s20
	s_sub_i32 s5, s5, s16
	s_mul_i32 s16, s28, 0x480
	s_mul_hi_u32 s17, s3, 0x480
	s_add_i32 s17, s17, s16
	s_mul_i32 s18, s3, 0x480
	s_mul_i32 s16, s5, 0x60
	s_add_u32 s18, s59, s18
	s_addc_u32 s19, s80, s17
	s_ashr_i32 s17, s16, 31
	s_lshl_b64 s[16:17], s[16:17], 1
	s_mul_hi_u32 s29, s20, 0x480
	s_mul_i32 s38, s21, 0x480
	s_add_u32 s18, s18, s16
	s_addc_u32 s19, s19, s17
	s_add_i32 s29, s29, s38
	s_mul_i32 s38, s20, 0x480
	s_add_u32 s38, s70, s38
	s_addc_u32 s29, s71, s29
	s_mul_hi_u32 s40, s20, 0x300
	s_mulk_i32 s21, 0x300
	s_add_u32 s38, s38, s16
	s_addc_u32 s39, s29, s17
	s_add_i32 s40, s40, s21
	s_mulk_i32 s20, 0x300
	s_add_u32 s29, s81, s20
	s_addc_u32 s41, s82, s40
	s_lshl_b32 s20, s5, 6
	s_ashr_i32 s21, s20, 31
	v_mov_b32_e32 v126, v253
	s_lshl_b64 s[20:21], s[20:21], 1
	v_lshlrev_b32_e32 v1, 3, v126
	s_add_u32 s40, s29, s20
	v_ashrrev_i32_e32 v127, 2, v126
	s_waitcnt vmcnt(8)
	v_and_b32_e32 v55, 24, v1
	v_lshlrev_b32_e32 v1, 4, v126
	v_mov_b64_e32 v[2:3], s[38:39]
	s_addc_u32 s41, s41, s21
	v_ashrrev_i32_e32 v129, 3, v126
	v_and_b32_e32 v22, 0x70, v1
	v_mov_b32_e32 v23, v0
	v_mad_i64_i32 v[2:3], s[38:39], v127, s91, v[2:3]
	v_lshlrev_b32_e32 v4, 1, v55
	v_mov_b32_e32 v5, v0
	v_add_u32_e32 v54, 64, v129
	v_lshl_add_u64 v[50:51], s[40:41], 0, v[22:23]
	v_lshl_add_u64 v[52:53], v[2:3], 0, v[4:5]
	v_mad_i64_i32 v[14:15], s[40:41], v54, s87, v[50:51]
	global_load_dwordx4 v[2:5], v[52:53], off offset:64
	global_load_dwordx4 v[6:9], v[52:53], off
	v_mad_i64_i32 v[16:17], s[38:39], v129, s87, v[50:51]
	global_load_dwordx4 v[10:13], v[52:53], off offset:128
	global_load_dwordx4 v[38:41], v[16:17], off
	global_load_dwordx4 v[42:45], v[14:15], off
	v_and_b32_e32 v130, 15, v126
	v_ashrrev_i32_e32 v14, 1, v126
	v_bfe_u32 v120, v126, 4, 2
	v_and_or_b32 v144, v14, s95, v130
	v_lshlrev_b32_e32 v24, 4, v120
	v_mov_b32_e32 v25, v0
	v_lshl_add_u64 v[18:19], s[18:19], 0, v[24:25]
	v_or_b32_e32 v142, 16, v144
	v_mad_i64_i32 v[34:35], s[18:19], v144, s91, v[18:19]
	v_mad_i64_i32 v[30:31], s[18:19], v142, s91, v[18:19]
	global_load_dwordx4 v[14:17], v[34:35], off
	global_load_dwordx4 v[18:21], v[30:31], off
	v_mul_lo_u32 v23, v127, s96
	v_and_b32_e32 v1, 48, v1
	v_mul_lo_u32 v25, v129, s89
	v_add_u32_e32 v23, 0, v23
	v_add_u32_e32 v22, 0, v22
	v_add_u32_e32 v128, 0, v24
	v_add_u32_e32 v1, v23, v1
	v_add_u32_e32 v143, v22, v25
	global_load_dwordx4 v[22:25], v[34:35], off offset:64
	global_load_dwordx4 v[26:29], v[30:31], off offset:128
	s_nop 0
	global_load_dwordx4 v[30:33], v[30:31], off offset:64
	s_nop 0
	global_load_dwordx4 v[34:37], v[34:35], off offset:128
	v_mad_u32_u24 v121, v130, s96, v128
	s_barrier
	v_lshlrev_b32_e32 v145, 2, v120
	v_add_u32_e32 v131, 0, v55
	s_mov_b32 s5, 0x24000
	s_mul_i32 s38, s2, 0x240000
	s_mov_b32 s29, 1
	s_waitcnt vmcnt(9)
	ds_write_b128 v1, v[6:9]
	ds_write_b128 v1, v[2:5] offset:64
	s_waitcnt vmcnt(8)
	ds_write_b128 v1, v[10:13] offset:128
	s_waitcnt vmcnt(7)
	ds_write_b128 v143, v[38:41] offset:32768
	s_waitcnt vmcnt(6)
	ds_write_b128 v143, v[42:45] offset:41984
	s_waitcnt lgkmcnt(0)
	s_barrier
	ds_read_b128 v[2:5], v121
	ds_read_b128 v[10:13], v121 offset:3328
	ds_read_b128 v[46:49], v121 offset:6656
	ds_read_b128 v[56:59], v121 offset:9984
	ds_read_b128 v[68:71], v121 offset:13312
	ds_read_b128 v[72:75], v121 offset:16640
	ds_read_b128 v[84:87], v121 offset:19968
	ds_read_b128 v[88:91], v121 offset:23296
	v_mov_b64_e32 v[6:7], s[44:45]
	v_mov_b64_e32 v[8:9], s[46:47]
	s_waitcnt vmcnt(5) lgkmcnt(7)
	s_nop 0
	v_mfma_f32_16x16x32_bf16 v[38:41], v[2:5], v[14:17], v[6:9]
	s_waitcnt vmcnt(4)
	v_mfma_f32_16x16x32_bf16 v[2:5], v[2:5], v[18:21], v[6:9]
	s_waitcnt lgkmcnt(6)
	v_mfma_f32_16x16x32_bf16 v[42:45], v[10:13], v[14:17], v[6:9]
	v_mfma_f32_16x16x32_bf16 v[10:13], v[10:13], v[18:21], v[6:9]
	s_waitcnt lgkmcnt(5)
	v_mfma_f32_16x16x32_bf16 v[60:63], v[46:49], v[14:17], v[6:9]
	v_mfma_f32_16x16x32_bf16 v[46:49], v[46:49], v[18:21], v[6:9]
	s_waitcnt lgkmcnt(4)
	v_mfma_f32_16x16x32_bf16 v[64:67], v[56:59], v[14:17], v[6:9]
	v_mfma_f32_16x16x32_bf16 v[56:59], v[56:59], v[18:21], v[6:9]
	s_waitcnt lgkmcnt(3)
	v_mfma_f32_16x16x32_bf16 v[76:79], v[68:71], v[14:17], v[6:9]
	v_mfma_f32_16x16x32_bf16 v[68:71], v[68:71], v[18:21], v[6:9]
	s_waitcnt lgkmcnt(2)
	v_mfma_f32_16x16x32_bf16 v[80:83], v[72:75], v[14:17], v[6:9]
	v_mfma_f32_16x16x32_bf16 v[72:75], v[72:75], v[18:21], v[6:9]
	s_waitcnt lgkmcnt(1)
	v_mfma_f32_16x16x32_bf16 v[92:95], v[84:87], v[14:17], v[6:9]
	v_mfma_f32_16x16x32_bf16 v[84:87], v[84:87], v[18:21], v[6:9]
	s_waitcnt lgkmcnt(0)
; #define LASP __attribute__((address_space(3)))
; template <int DQK>
; __device__ __forceinline__ void flash_item(unsigned char* smem, const bf16_t* Q, int qs, const bf16_t* K0, const bf16_t* V0, int n0, const bf16_t* K1, const bf16_t* V1, int n1, int ks, int vs, bf16_t* Oo, int os, float shift) {
;     ...
;         for (int kk = 0; kk < NKK; ++kk) {
; #pragma unroll
;             for (int kg = 0; kg < NKG; ++kg) {
;                 const bf16x8_t kf = *(const LASP bf16x8_t*)(ls + (kg * 16 + fr) * KR + (kk * 32 + fq * 8) * 2);
;                 s[kg][0] = __builtin_amdgcn_mfma_f32_16x16x32_bf16(kf, qf[0][kk], s[kg][0], 0, 0, 0);
;                 s[kg][1] = __builtin_amdgcn_mfma_f32_16x16x32_bf16(kf, qf[1][kk], s[kg][1], 0, 0, 0);
;             }
;             asm volatile("" ::: "memory");
;         }
;         if (t + 1 < ntiles) FL_LOAD((t + 1) * KT);
; #pragma unroll
;         for (int qg = 0; qg < 2; ++qg) {
;             float ps = 0.f;
; #pragma unroll
;             for (int kg = 0; kg < NKG; ++kg)
; #pragma unroll
;                 for (int j = 0; j < 4; ++j) { const float p = __builtin_amdgcn_exp2f(s[kg][qg][j]); s[kg][qg][j] = p; ps += p; }
;             lsum[qg] += ps;
;         }
; #pragma unroll
;         for (int kp = 0; kp < NKP; ++kp) {
;             bf16x8_t pb[2];
; #pragma unroll
;             for (int qg = 0; qg < 2; ++qg) {
;                 const f32x4_t a = s[2 * kp][qg], b = s[2 * kp + 1][qg];
;                 u32x4_t pk; pk.x = pg8::cvt_pk_bf16(a[0], a[1]); pk.y = pg8::cvt_pk_bf16(a[2], a[3]); pk.z = pg8::cvt_pk_bf16(b[0], b[1]); pk.w = pg8::cvt_pk_bf16(b[2], b[3]);
;                 pb[qg] = __builtin_bit_cast(bf16x8_t, pk);
;             }
; #pragma unroll
;             for (int dg = 0; dg < 4; ++dg) {
;                 LASP unsigned char* va = ls + VOFF + (32 * kp + 4 * fq + (fr >> 2)) * VR + (16 * dg + 4 * (fr & 3)) * 2;
;                 const s16x4 v0 = __builtin_amdgcn_ds_read_tr16_b64_v4i16((LASP s16x4*)va);
;                 const s16x4 v1 = __builtin_amdgcn_ds_read_tr16_b64_v4i16((LASP s16x4*)(va + 16 * VR));
;                 const bf16x8_t vf = __builtin_shufflevector(v0, v1, 0, 1, 2, 3, 4, 5, 6, 7);
;                 o[dg][0] = __builtin_amdgcn_mfma_f32_16x16x32_bf16(vf, pb[0], o[dg][0], 0, 0, 0);
;                 o[dg][1] = __builtin_amdgcn_mfma_f32_16x16x32_bf16(vf, pb[1], o[dg][1], 0, 0, 0);
;             }
	v_mfma_f32_16x16x32_bf16 v[96:99], v[88:91], v[14:17], v[6:9]
	v_mfma_f32_16x16x32_bf16 v[6:9], v[88:91], v[18:21], v[6:9]
	ds_read_b128 v[88:91], v121 offset:64
	ds_read_b128 v[100:103], v121 offset:3392
	s_waitcnt vmcnt(3) lgkmcnt(1)
	v_mfma_f32_16x16x32_bf16 v[38:41], v[88:91], v[22:25], v[38:41]
	s_waitcnt vmcnt(1)
	v_mfma_f32_16x16x32_bf16 v[2:5], v[88:91], v[30:33], v[2:5]
	s_waitcnt lgkmcnt(0)
	v_mfma_f32_16x16x32_bf16 v[42:45], v[100:103], v[22:25], v[42:45]
	v_mfma_f32_16x16x32_bf16 v[10:13], v[100:103], v[30:33], v[10:13]
	ds_read_b128 v[88:91], v121 offset:6720
	ds_read_b128 v[100:103], v121 offset:10048
	s_waitcnt lgkmcnt(1)
	v_mfma_f32_16x16x32_bf16 v[60:63], v[88:91], v[22:25], v[60:63]
	v_mfma_f32_16x16x32_bf16 v[46:49], v[88:91], v[30:33], v[46:49]
	s_waitcnt lgkmcnt(0)
	v_mfma_f32_16x16x32_bf16 v[64:67], v[100:103], v[22:25], v[64:67]
	v_mfma_f32_16x16x32_bf16 v[56:59], v[100:103], v[30:33], v[56:59]
	ds_read_b128 v[88:91], v121 offset:13376
	ds_read_b128 v[100:103], v121 offset:16704
	s_waitcnt lgkmcnt(1)
	v_mfma_f32_16x16x32_bf16 v[76:79], v[88:91], v[22:25], v[76:79]
	v_mfma_f32_16x16x32_bf16 v[68:71], v[88:91], v[30:33], v[68:71]
	s_waitcnt lgkmcnt(0)
	v_mfma_f32_16x16x32_bf16 v[80:83], v[100:103], v[22:25], v[80:83]
	v_mfma_f32_16x16x32_bf16 v[72:75], v[100:103], v[30:33], v[72:75]
	ds_read_b128 v[88:91], v121 offset:20032
	ds_read_b128 v[100:103], v121 offset:23360
	s_waitcnt lgkmcnt(1)
	v_mfma_f32_16x16x32_bf16 v[92:95], v[88:91], v[22:25], v[92:95]
	v_mfma_f32_16x16x32_bf16 v[84:87], v[88:91], v[30:33], v[84:87]
	s_waitcnt lgkmcnt(0)
	v_mfma_f32_16x16x32_bf16 v[88:91], v[100:103], v[22:25], v[96:99]
	v_mfma_f32_16x16x32_bf16 v[96:99], v[100:103], v[30:33], v[6:9]
	s_nop 2
	ds_read_b128 v[6:9], v121 offset:128
	ds_read_b128 v[100:103], v121 offset:3456
	s_waitcnt vmcnt(0) lgkmcnt(1)
	v_mfma_f32_16x16x32_bf16 v[104:107], v[6:9], v[34:37], v[38:41]
	v_mfma_f32_16x16x32_bf16 v[108:111], v[6:9], v[26:29], v[2:5]
	s_nop 2
	ds_read_b128 v[2:5], v121 offset:6784
	ds_read_b128 v[6:9], v121 offset:10112
	s_waitcnt lgkmcnt(1)
	v_mfma_f32_16x16x32_bf16 v[60:63], v[2:5], v[34:37], v[60:63]
	v_mfma_f32_16x16x32_bf16 v[116:119], v[2:5], v[26:29], v[46:49]
	s_waitcnt lgkmcnt(0)
	v_mfma_f32_16x16x32_bf16 v[64:67], v[6:9], v[34:37], v[64:67]
	v_mfma_f32_16x16x32_bf16 v[56:59], v[6:9], v[26:29], v[56:59]
	ds_read_b128 v[2:5], v121 offset:13440
	ds_read_b128 v[6:9], v121 offset:16768
	v_mfma_f32_16x16x32_bf16 v[112:115], v[100:103], v[34:37], v[42:45]
	s_waitcnt lgkmcnt(1)
	v_mfma_f32_16x16x32_bf16 v[132:135], v[2:5], v[34:37], v[76:79]
	v_mfma_f32_16x16x32_bf16 v[46:49], v[2:5], v[26:29], v[68:71]
	s_nop 4
	v_exp_f32_e32 v79, v115
	s_nop 0
	v_exp_f32_e32 v125, v132
	v_lshl_add_u64 v[76:77], v[52:53], 0, s[14:15]
	s_waitcnt lgkmcnt(0)
	v_mfma_f32_16x16x32_bf16 v[42:45], v[6:9], v[26:29], v[72:75]
	ds_read_b128 v[2:5], v121 offset:20096
	s_nop 1
	ds_read_b128 v[72:75], v121 offset:23424
	v_exp_f32_e32 v124, v46
	v_mfma_f32_16x16x32_bf16 v[100:103], v[100:103], v[26:29], v[10:13]
	v_mfma_f32_16x16x32_bf16 v[68:71], v[6:9], v[34:37], v[80:83]
	s_waitcnt lgkmcnt(1)
	v_mfma_f32_16x16x32_bf16 v[38:41], v[2:5], v[34:37], v[92:95]
	s_nop 0
	v_exp_f32_e32 v83, v113
	v_exp_f32_e32 v81, v114
	s_nop 1
	v_exp_f32_e32 v82, v101
	v_mfma_f32_16x16x32_bf16 v[6:9], v[2:5], v[26:29], v[84:87]
	v_bfe_u32 v2, v126, 2, 2
	v_or_b32_e32 v194, v145, v2
	v_mad_u32_u24 v55, v194, s89, v131
	s_waitcnt lgkmcnt(0)
	v_mfma_f32_16x16x32_bf16 v[10:13], v[72:75], v[34:37], v[88:91]
	v_exp_f32_e32 v93, v104
	v_exp_f32_e32 v87, v107
	v_exp_f32_e32 v85, v112
	v_mfma_f32_16x16x32_bf16 v[2:5], v[72:75], v[26:29], v[96:99]
	v_exp_f32_e32 v91, v105
	v_exp_f32_e32 v89, v106
	v_exp_f32_e32 v92, v108
	v_exp_f32_e32 v90, v109
	v_exp_f32_e32 v88, v110
	v_exp_f32_e32 v86, v111
	v_exp_f32_e32 v84, v100
	v_exp_f32_e32 v80, v102
	v_exp_f32_e32 v78, v103
	ds_read_b64_tr_b16 v[96:97], v55 offset:35072
	ds_read_b64_tr_b16 v[94:95], v55 offset:32768
	ds_read_b64_tr_b16 v[98:99], v55 offset:32800
	ds_read_b64_tr_b16 v[120:121], v55 offset:32832
	ds_read_b64_tr_b16 v[136:137], v55 offset:32864
	ds_read_b64_tr_b16 v[100:101], v55 offset:35104
	ds_read_b64_tr_b16 v[122:123], v55 offset:35136
	ds_read_b64_tr_b16 v[138:139], v55 offset:35168
	v_cvt_pk_bf16_f32 v72, v93, v91
	v_cvt_pk_bf16_f32 v73, v89, v87
	v_cvt_pk_bf16_f32 v74, v85, v83
	v_cvt_pk_bf16_f32 v75, v81, v79
	v_cvt_pk_bf16_f32 v110, v92, v90
	v_cvt_pk_bf16_f32 v111, v88, v86
	v_cvt_pk_bf16_f32 v112, v84, v82
	v_cvt_pk_bf16_f32 v113, v80, v78
	s_waitcnt lgkmcnt(6)
	v_mfma_f32_16x16x32_bf16 v[146:149], v[94:97], v[72:75], 0
	v_exp_f32_e32 v109, v60
	v_exp_f32_e32 v107, v61
	v_exp_f32_e32 v105, v62
	v_mfma_f32_16x16x32_bf16 v[150:153], v[94:97], v[110:113], 0
	v_exp_f32_e32 v103, v63
	v_exp_f32_e32 v97, v66
	v_exp_f32_e32 v95, v67
	s_waitcnt lgkmcnt(2)
	v_mfma_f32_16x16x32_bf16 v[156:159], v[98:101], v[72:75], 0
	v_exp_f32_e32 v108, v116
	v_exp_f32_e32 v106, v117
	v_exp_f32_e32 v104, v118
	v_mfma_f32_16x16x32_bf16 v[60:63], v[98:101], v[110:113], 0
	v_exp_f32_e32 v101, v64
	v_exp_f32_e32 v99, v65
	v_exp_f32_e32 v102, v119
	s_waitcnt lgkmcnt(1)
	v_mfma_f32_16x16x32_bf16 v[64:67], v[120:123], v[110:113], 0
	v_exp_f32_e32 v100, v56
	v_exp_f32_e32 v98, v57
	v_exp_f32_e32 v96, v58
	v_exp_f32_e32 v94, v59
	s_waitcnt lgkmcnt(0)
; __device__ __forceinline__ unsigned cvt_pk_bf16(float lo, float hi) { const f32x2c f = {lo, hi}; return __builtin_bit_cast(unsigned, __builtin_convertvector(f, bf16x2c)); }
; #define LASP __attribute__((address_space(3)))
; template <int DQK>
; __device__ __forceinline__ void flash_item(unsigned char* smem, const bf16_t* Q, int qs, const bf16_t* K0, const bf16_t* V0, int n0, const bf16_t* K1, const bf16_t* V1, int n1, int ks, int vs, bf16_t* Oo, int os, float shift) {
;     ...
;         for (int kp = 0; kp < NKP; ++kp) {
;             bf16x8_t pb[2];
; #pragma unroll
;             for (int qg = 0; qg < 2; ++qg) {
;                 const f32x4_t a = s[2 * kp][qg], b = s[2 * kp + 1][qg];
;                 u32x4_t pk; pk.x = pg8::cvt_pk_bf16(a[0], a[1]); pk.y = pg8::cvt_pk_bf16(a[2], a[3]); pk.z = pg8::cvt_pk_bf16(b[0], b[1]); pk.w = pg8::cvt_pk_bf16(b[2], b[3]);
;                 pb[qg] = __builtin_bit_cast(bf16x8_t, pk);
;             }
; #pragma unroll
;             for (int dg = 0; dg < 4; ++dg) {
;                 LASP unsigned char* va = ls + VOFF + (32 * kp + 4 * fq + (fr >> 2)) * VR + (16 * dg + 4 * (fr & 3)) * 2;
;                 const s16x4 v0 = __builtin_amdgcn_ds_read_tr16_b64_v4i16((LASP s16x4*)va);
;                 const s16x4 v1 = __builtin_amdgcn_ds_read_tr16_b64_v4i16((LASP s16x4*)(va + 16 * VR));
;                 const bf16x8_t vf = __builtin_shufflevector(v0, v1, 0, 1, 2, 3, 4, 5, 6, 7);
;                 o[dg][0] = __builtin_amdgcn_mfma_f32_16x16x32_bf16(vf, pb[0], o[dg][0], 0, 0, 0);
;                 o[dg][1] = __builtin_amdgcn_mfma_f32_16x16x32_bf16(vf, pb[1], o[dg][1], 0, 0, 0);
;             }
	v_mfma_f32_16x16x32_bf16 v[56:59], v[136:139], v[110:113], 0
	ds_read_b64_tr_b16 v[110:111], v55 offset:37376
	ds_read_b64_tr_b16 v[112:113], v55 offset:39680
	ds_read_b64_tr_b16 v[114:115], v55 offset:37408
	ds_read_b64_tr_b16 v[168:169], v55 offset:37440
	ds_read_b64_tr_b16 v[172:173], v55 offset:37472
	ds_read_b64_tr_b16 v[116:117], v55 offset:39712
	ds_read_b64_tr_b16 v[170:171], v55 offset:39744
	ds_read_b64_tr_b16 v[174:175], v55 offset:39776
	v_cvt_pk_bf16_f32 v164, v108, v106
	v_mfma_f32_16x16x32_bf16 v[160:163], v[120:123], v[72:75], 0
	v_cvt_pk_bf16_f32 v165, v104, v102
	v_cvt_pk_bf16_f32 v166, v100, v98
	v_cvt_pk_bf16_f32 v167, v96, v94
	v_mfma_f32_16x16x32_bf16 v[72:75], v[136:139], v[72:75], 0
	v_cvt_pk_bf16_f32 v136, v109, v107
	v_cvt_pk_bf16_f32 v137, v105, v103
	v_cvt_pk_bf16_f32 v138, v101, v99
	v_cvt_pk_bf16_f32 v139, v97, v95
	s_waitcnt lgkmcnt(6)
	v_mfma_f32_16x16x32_bf16 v[150:153], v[110:113], v[164:167], v[150:153]
	v_exp_f32_e32 v123, v133
	v_exp_f32_e32 v121, v134
	v_exp_f32_e32 v119, v135
	v_mfma_f32_16x16x32_bf16 v[146:149], v[110:113], v[136:139], v[146:149]
	v_exp_f32_e32 v113, v70
	v_exp_f32_e32 v111, v71
	v_exp_f32_e32 v122, v47
	s_waitcnt lgkmcnt(2)
	v_mfma_f32_16x16x32_bf16 v[156:159], v[114:117], v[136:139], v[156:159]
	v_exp_f32_e32 v120, v48
	v_exp_f32_e32 v118, v49
	v_exp_f32_e32 v112, v44
	v_mfma_f32_16x16x32_bf16 v[60:63], v[114:117], v[164:167], v[60:63]
	v_exp_f32_e32 v117, v68
	v_exp_f32_e32 v115, v69
	v_exp_f32_e32 v116, v42
	v_exp_f32_e32 v114, v43
	v_exp_f32_e32 v110, v45
	ds_read_b64_tr_b16 v[68:69], v55 offset:41984
	ds_read_b64_tr_b16 v[70:71], v55 offset:44288
	s_waitcnt lgkmcnt(3)
	v_mfma_f32_16x16x32_bf16 v[132:135], v[168:171], v[136:139], v[160:163]
	v_exp_f32_e32 v141, v38
	v_exp_f32_e32 v181, v39
	v_exp_f32_e32 v183, v40
	v_mfma_f32_16x16x32_bf16 v[64:67], v[168:171], v[164:167], v[64:67]
	v_exp_f32_e32 v185, v41
	v_exp_f32_e32 v187, v10
	v_exp_f32_e32 v189, v11
	s_waitcnt lgkmcnt(2)
	v_mfma_f32_16x16x32_bf16 v[46:49], v[172:175], v[136:139], v[72:75]
	v_exp_f32_e32 v191, v12
	v_exp_f32_e32 v193, v13
	v_exp_f32_e32 v140, v6
	v_mfma_f32_16x16x32_bf16 v[42:45], v[172:175], v[164:167], v[56:59]
	ds_read_b64_tr_b16 v[136:137], v55 offset:42016
	ds_read_b64_tr_b16 v[160:161], v55 offset:42048
	ds_read_b64_tr_b16 v[164:165], v55 offset:42080
	ds_read_b64_tr_b16 v[138:139], v55 offset:44320
	ds_read_b64_tr_b16 v[162:163], v55 offset:44352
	ds_read_b64_tr_b16 v[166:167], v55 offset:44384
	v_cvt_pk_bf16_f32 v56, v125, v123
	v_cvt_pk_bf16_f32 v57, v121, v119
	v_cvt_pk_bf16_f32 v58, v117, v115
	v_cvt_pk_bf16_f32 v59, v113, v111
	v_cvt_pk_bf16_f32 v72, v124, v122
	v_cvt_pk_bf16_f32 v73, v120, v118
	v_cvt_pk_bf16_f32 v74, v116, v114
	v_cvt_pk_bf16_f32 v75, v112, v110
	v_exp_f32_e32 v180, v7
	v_exp_f32_e32 v182, v8
	v_exp_f32_e32 v184, v9
	v_exp_f32_e32 v186, v2
	v_exp_f32_e32 v188, v3
	v_exp_f32_e32 v190, v4
	v_exp_f32_e32 v192, v5
	ds_read_b64_tr_b16 v[2:3], v55 offset:46592
	ds_read_b64_tr_b16 v[4:5], v55 offset:48896
	s_waitcnt lgkmcnt(8)
	v_mfma_f32_16x16x32_bf16 v[146:149], v[68:71], v[56:59], v[146:149]
	ds_read_b64_tr_b16 v[6:7], v55 offset:46624
	ds_read_b64_tr_b16 v[172:173], v55 offset:46656
	ds_read_b64_tr_b16 v[176:177], v55 offset:46688
	ds_read_b64_tr_b16 v[8:9], v55 offset:48928
	ds_read_b64_tr_b16 v[174:175], v55 offset:48960
	ds_read_b64_tr_b16 v[178:179], v55 offset:48992
	v_cvt_pk_bf16_f32 v168, v140, v180
	v_cvt_pk_bf16_f32 v169, v182, v184
	v_mfma_f32_16x16x32_bf16 v[68:71], v[68:71], v[72:75], v[150:153]
	v_cvt_pk_bf16_f32 v170, v186, v188
	v_cvt_pk_bf16_f32 v171, v190, v192
	v_pk_add_f32 v[92:93], v[92:93], 0 op_sel_hi:[1,0]
	s_waitcnt lgkmcnt(10)
	v_mfma_f32_16x16x32_bf16 v[150:153], v[136:139], v[56:59], v[156:159]
	v_add_f32_e64 v90, v90, v92
	v_add_f32_e64 v91, v91, v93
	v_pk_add_f32 v[88:89], v[88:89], v[90:91]
	v_mfma_f32_16x16x32_bf16 v[136:139], v[136:139], v[72:75], v[60:63]
	v_add_f32_e64 v86, v86, v88
	v_add_f32_e64 v87, v87, v89
	v_pk_add_f32 v[84:85], v[84:85], v[86:87]
	s_waitcnt lgkmcnt(9)
; __device__ __forceinline__ unsigned cvt_pk_bf16(float lo, float hi) { const f32x2c f = {lo, hi}; return __builtin_bit_cast(unsigned, __builtin_convertvector(f, bf16x2c)); }
; #define LASP __attribute__((address_space(3)))
; template <int DQK>
; __device__ __forceinline__ void flash_item(unsigned char* smem, const bf16_t* Q, int qs, const bf16_t* K0, const bf16_t* V0, int n0, const bf16_t* K1, const bf16_t* V1, int n1, int ks, int vs, bf16_t* Oo, int os, float shift) {
;     ...
;         __syncthreads();
; #pragma unroll
;         for (int c = 0; c < NKC; ++c) *(LASP u32x4_t*)(ls + (tid >> 2) * KR + ((tid & 3) + 4 * c) * 16) = kreg[c];
; #pragma unroll
;         for (int c = 0; c < NVC; ++c) *(LASP u32x4_t*)(ls + VOFF + ((tid >> 3) + 64 * c) * VR + (tid & 7) * 16) = vreg[c];
;         __syncthreads();
;     ...
;         if (t + 1 < ntiles) FL_LOAD((t + 1) * KT);
; #pragma unroll
;         for (int qg = 0; qg < 2; ++qg) {
;             float ps = 0.f;
; #pragma unroll
;             for (int kg = 0; kg < NKG; ++kg)
; #pragma unroll
;                 for (int j = 0; j < 4; ++j) { const float p = __builtin_amdgcn_exp2f(s[kg][qg][j]); s[kg][qg][j] = p; ps += p; }
;             lsum[qg] += ps;
;         }
; #pragma unroll
;         for (int kp = 0; kp < NKP; ++kp) {
;             bf16x8_t pb[2];
; #pragma unroll
;             for (int qg = 0; qg < 2; ++qg) {
;                 const f32x4_t a = s[2 * kp][qg], b = s[2 * kp + 1][qg];
;                 u32x4_t pk; pk.x = pg8::cvt_pk_bf16(a[0], a[1]); pk.y = pg8::cvt_pk_bf16(a[2], a[3]); pk.z = pg8::cvt_pk_bf16(b[0], b[1]); pk.w = pg8::cvt_pk_bf16(b[2], b[3]);
;                 pb[qg] = __builtin_bit_cast(bf16x8_t, pk);
;             }
; #pragma unroll
;             for (int dg = 0; dg < 4; ++dg) {
;                 LASP unsigned char* va = ls + VOFF + (32 * kp + 4 * fq + (fr >> 2)) * VR + (16 * dg + 4 * (fr & 3)) * 2;
;                 const s16x4 v0 = __builtin_amdgcn_ds_read_tr16_b64_v4i16((LASP s16x4*)va);
;                 const s16x4 v1 = __builtin_amdgcn_ds_read_tr16_b64_v4i16((LASP s16x4*)(va + 16 * VR));
;                 const bf16x8_t vf = __builtin_shufflevector(v0, v1, 0, 1, 2, 3, 4, 5, 6, 7);
;                 o[dg][0] = __builtin_amdgcn_mfma_f32_16x16x32_bf16(vf, pb[0], o[dg][0], 0, 0, 0);
;                 o[dg][1] = __builtin_amdgcn_mfma_f32_16x16x32_bf16(vf, pb[1], o[dg][1], 0, 0, 0);
;             }
	v_mfma_f32_16x16x32_bf16 v[132:135], v[160:163], v[56:59], v[132:135]
	v_add_f32_e64 v82, v82, v84
	v_add_f32_e64 v83, v83, v85
	v_pk_add_f32 v[80:81], v[80:81], v[82:83]
	v_mfma_f32_16x16x32_bf16 v[10:13], v[160:163], v[72:75], v[64:67]
	v_add_f32_e64 v78, v78, v80
	v_add_f32_e64 v79, v79, v81
	v_and_b32_e32 v80, 7, v126
	v_pk_add_f32 v[78:79], v[108:109], v[78:79]
	s_waitcnt lgkmcnt(8)
	v_mfma_f32_16x16x32_bf16 v[156:159], v[164:167], v[56:59], v[46:49]
	v_lshl_add_u64 v[56:57], v[50:51], 0, s[36:37]
	global_load_dwordx4 v[38:41], v[76:77], off offset:64
	s_nop 0
	global_load_dwordx4 v[46:49], v[76:77], off offset:128
	v_mad_i64_i32 v[50:51], s[18:19], v129, s87, v[56:57]
	v_mfma_f32_16x16x32_bf16 v[160:163], v[164:167], v[72:75], v[42:45]
	v_cvt_pk_bf16_f32 v164, v141, v181
	v_cvt_pk_bf16_f32 v165, v183, v185
	v_cvt_pk_bf16_f32 v166, v187, v189
	v_cvt_pk_bf16_f32 v167, v191, v193
	v_add_co_u32_e32 v42, vcc, s5, v52
	s_waitcnt lgkmcnt(6)
	v_mfma_f32_16x16x32_bf16 v[62:65], v[2:5], v[164:167], v[146:149]
	v_addc_co_u32_e32 v43, vcc, 0, v53, vcc
	global_load_dwordx4 v[42:45], v[42:43], off
	s_nop 0
	global_load_dwordx4 v[50:53], v[50:51], off
	v_mfma_f32_16x16x32_bf16 v[58:61], v[2:5], v[168:171], v[68:71]
	v_add_f32_e64 v78, v106, v78
	v_add_f32_e64 v79, v107, v79
	s_mul_hi_i32 s5, s2, 0x240000
	v_pk_add_f32 v[78:79], v[104:105], v[78:79]
	s_waitcnt lgkmcnt(2)
	v_mfma_f32_16x16x32_bf16 v[74:77], v[6:9], v[164:167], v[150:153]
	v_add_f32_e64 v78, v102, v78
	v_add_f32_e64 v79, v103, v79
	v_pk_add_f32 v[78:79], v[100:101], v[78:79]
	v_mfma_f32_16x16x32_bf16 v[2:5], v[6:9], v[168:171], v[136:139]
	v_mad_i64_i32 v[6:7], s[18:19], v54, s87, v[56:57]
	global_load_dwordx4 v[54:57], v[6:7], off
	v_pk_add_f32 v[78:79], v[98:99], v[78:79]
	s_waitcnt lgkmcnt(1)
	v_mfma_f32_16x16x32_bf16 v[70:73], v[172:175], v[164:167], v[132:135]
	v_add_f32_e64 v78, v96, v78
	v_add_f32_e64 v79, v97, v79
	v_pk_add_f32 v[78:79], v[94:95], v[78:79]
	s_waitcnt lgkmcnt(0)
	v_mfma_f32_16x16x32_bf16 v[66:69], v[176:179], v[164:167], v[156:159]
	v_add_f32_e64 v78, v124, v78
	v_add_f32_e64 v79, v125, v79
	v_mad_i64_i32 v[132:133], s[18:19], v129, s87, 0
	v_pk_add_f32 v[78:79], v[122:123], v[78:79]
	v_mfma_f32_16x16x32_bf16 v[6:9], v[172:175], v[168:171], v[10:13]
	v_add_f32_e64 v78, v120, v78
	v_add_f32_e64 v79, v121, v79
	v_mul_u32_u24_e32 v129, 0xd0, v130
	v_pk_add_f32 v[78:79], v[118:119], v[78:79]
	v_mfma_f32_16x16x32_bf16 v[10:13], v[176:179], v[168:171], v[160:163]
	v_add_f32_e64 v78, v116, v78
	v_add_f32_e64 v79, v117, v79
	v_mul_u32_u24_e32 v130, 0x90, v194
	v_pk_add_f32 v[78:79], v[114:115], v[78:79]
	v_add_u32_e32 v162, v128, v129
	v_pk_add_f32 v[78:79], v[112:113], v[78:79]
	v_add_u32_e32 v163, v131, v130
	v_pk_add_f32 v[78:79], v[110:111], v[78:79]
	s_nop 0
	v_pk_add_f32 v[78:79], v[140:141], v[78:79]
	s_nop 0
	v_pk_add_f32 v[78:79], v[180:181], v[78:79]
	s_nop 0
	v_pk_add_f32 v[78:79], v[182:183], v[78:79]
	s_nop 0
	v_pk_add_f32 v[78:79], v[184:185], v[78:79]
	s_nop 0
	v_pk_add_f32 v[78:79], v[186:187], v[78:79]
	s_nop 0
	v_pk_add_f32 v[78:79], v[188:189], v[78:79]
	s_nop 0
	v_pk_add_f32 v[78:79], v[190:191], v[78:79]
	s_nop 0
	v_pk_add_f32 v[78:79], v[192:193], v[78:79]
	s_nop 0
	v_pk_add_f32 v[156:157], v[78:79], 0 op_sel_hi:[1,0]
	v_mov_b32_e32 v78, 0x180000
	v_mad_i64_i32 v[78:79], s[18:19], s2, v78, v[132:133]
	s_add_u32 s18, s38, 0x19418040
	v_lshl_or_b32 v78, v80, 4, v78
	s_addc_u32 s19, s5, 0
	v_lshl_add_u64 v[158:159], v[78:79], 0, s[20:21]
	v_mov_b64_e32 v[78:79], s[18:19]
	v_mad_i64_i32 v[78:79], s[18:19], v127, s91, v[78:79]
	v_and_b32_e32 v80, 3, v126
	v_lshl_or_b32 v78, v80, 4, v78
	v_lshl_add_u64 v[160:161], v[78:79], 0, s[16:17]
	v_xor_b32_e32 v1, 0x10000, v1
	v_xor_b32_e32 v143, 0x10000, v143
	s_waitcnt vmcnt(2)
	ds_write_b128 v1, v[42:45]
	ds_write_b128 v1, v[38:41] offset:64
	ds_write_b128 v1, v[46:49] offset:128
	s_waitcnt vmcnt(1)
	ds_write_b128 v143, v[50:53] offset:32768
	s_waitcnt vmcnt(0)
	ds_write_b128 v143, v[54:57] offset:41984
	v_xor_b32_e32 v162, 0x10000, v162
	v_xor_b32_e32 v163, 0x10000, v163
	s_waitcnt lgkmcnt(0)
	s_barrier
	s_branch .LBB0_832

; template <int K> __device__ __forceinline__ float swz(float v) { return __int_as_float(__builtin_amdgcn_ds_swizzle(__float_as_int(v), (K << 10) | 0x1f)); }
; __device__ __forceinline__ float x32_sum(float v) { auto r = __builtin_amdgcn_permlane32_swap(__float_as_uint(v), __float_as_uint(v), false, false); return __uint_as_float(r[0]) + __uint_as_float(r[1]); }
; __device__ __forceinline__ unsigned cvt_pk_bf16(float lo, float hi) { const f32x2c f = {lo, hi}; return __builtin_bit_cast(unsigned, __builtin_convertvector(f, bf16x2c)); }
; template <int DQK>
; __device__ __forceinline__ void flash_item(unsigned char* smem, const bf16_t* Q, int qs, const bf16_t* K0, const bf16_t* V0, int n0, const bf16_t* K1, const bf16_t* V1, int n1, int ks, int vs, bf16_t* Oo, int os, float shift) {
;     ...
; #pragma unroll
;     for (int qg = 0; qg < 2; ++qg) {
;         float l = lsum[qg]; l += swz<16>(l); l = x32_sum(l);
;         const float inv = 1.0f / l;
;         bf16_t* orow = Oo + (size_t)(wave * 32 + qg * 16 + fr) * os + fq * 4;
; #pragma unroll
;         for (int dg = 0; dg < 4; ++dg) {
;             u32x2_t w; w.x = pg8::cvt_pk_bf16(o[dg][qg][0] * inv, o[dg][qg][1] * inv); w.y = pg8::cvt_pk_bf16(o[dg][qg][2] * inv, o[dg][qg][3] * inv);
;             *(u32x2_t*)(orow + dg * 16) = w;
;         }
;     }
.LBB0_834:
	s_setprio 0
	ds_swizzle_b32 v1, v157 offset:swizzle(SWAP,16)
	s_mul_i32 s2, s28, 0xa00
	s_mul_hi_u32 s5, s3, 0xa00
	s_add_i32 s5, s5, s2
	s_mul_i32 s2, s3, 0xa00
	s_waitcnt lgkmcnt(0)
	v_add_f32_e32 v1, v157, v1
	v_mov_b32_e32 v14, v1
	s_nop 1
	v_permlane32_swap_b32_e32 v1, v14
	v_add_f32_e32 v1, v1, v14
	v_div_scale_f32 v16, s[16:17], v1, v1, 1.0
	v_rcp_f32_e32 v17, v16
	s_add_u32 s2, s66, s2
	s_addc_u32 s3, s67, s5
	s_add_u32 s2, s2, s20
	v_fma_f32 v18, -v16, v17, 1.0
	v_fmac_f32_e32 v17, v18, v17
	v_div_scale_f32 v18, vcc, 1.0, v1, 1.0
	v_mul_f32_e32 v19, v18, v17
	v_fma_f32 v20, -v16, v19, v18
	v_fmac_f32_e32 v19, v20, v17
	v_fma_f32 v16, -v16, v19, v18
	v_div_fmas_f32 v16, v16, v17, v19
	s_addc_u32 s3, s3, s21
	v_lshlrev_b32_e32 v14, 1, v145
	v_mov_b32_e32 v15, v0
	v_div_fixup_f32 v16, v16, v1, 1.0
	v_lshl_add_u64 v[14:15], s[2:3], 0, v[14:15]
	v_pk_mul_f32 v[20:21], v[62:63], v[16:17] op_sel_hi:[1,0]
	v_pk_mul_f32 v[22:23], v[64:65], v[16:17] op_sel_hi:[1,0]
	ds_swizzle_b32 v1, v156 offset:swizzle(SWAP,16)
	v_mad_i64_i32 v[18:19], s[2:3], v144, s93, v[14:15]
	v_cvt_pk_bf16_f32 v20, v20, v21
	v_cvt_pk_bf16_f32 v21, v22, v23
	global_store_dwordx2 v[18:19], v[20:21], off offset:768
	v_pk_mul_f32 v[20:21], v[74:75], v[16:17] op_sel_hi:[1,0]
	v_pk_mul_f32 v[22:23], v[76:77], v[16:17] op_sel_hi:[1,0]
	v_cvt_pk_bf16_f32 v20, v20, v21
	v_cvt_pk_bf16_f32 v21, v22, v23
	global_store_dwordx2 v[18:19], v[20:21], off offset:800
	v_pk_mul_f32 v[20:21], v[70:71], v[16:17] op_sel_hi:[1,0]
	v_pk_mul_f32 v[22:23], v[72:73], v[16:17] op_sel_hi:[1,0]
	v_cvt_pk_bf16_f32 v20, v20, v21
	v_cvt_pk_bf16_f32 v21, v22, v23
	s_waitcnt lgkmcnt(0)
	v_add_f32_e32 v1, v156, v1
	global_store_dwordx2 v[18:19], v[20:21], off offset:832
	v_pk_mul_f32 v[20:21], v[66:67], v[16:17] op_sel_hi:[1,0]
	v_mov_b32_e32 v17, v1
	s_nop 1
	v_permlane32_swap_b32_e32 v1, v17
	v_add_f32_e32 v1, v1, v17
	v_div_scale_f32 v22, s[2:3], v1, v1, 1.0
	v_rcp_f32_e32 v23, v22
	v_pk_mul_f32 v[16:17], v[68:69], v[16:17] op_sel_hi:[1,0]
	v_cvt_pk_bf16_f32 v20, v20, v21
	v_cvt_pk_bf16_f32 v21, v16, v17
	v_fma_f32 v16, -v22, v23, 1.0
	v_fmac_f32_e32 v23, v16, v23
	v_div_scale_f32 v16, vcc, 1.0, v1, 1.0
	v_mul_f32_e32 v17, v16, v23
	global_store_dwordx2 v[18:19], v[20:21], off offset:864
	v_fma_f32 v18, -v22, v17, v16
	v_fmac_f32_e32 v17, v18, v23
	v_fma_f32 v16, -v22, v17, v16
	v_div_fmas_f32 v16, v16, v23, v17
	v_div_fixup_f32 v18, v16, v1, 1.0
	v_mad_i64_i32 v[14:15], s[2:3], v142, s93, v[14:15]
	v_pk_mul_f32 v[16:17], v[58:59], v[18:19] op_sel_hi:[1,0]
	v_pk_mul_f32 v[22:23], v[60:61], v[18:19] op_sel_hi:[1,0]
	s_mov_b64 s[2:3], 0x300
	v_cvt_pk_bf16_f32 v16, v16, v17
	v_cvt_pk_bf16_f32 v17, v22, v23
	v_lshl_add_u64 v[20:21], v[14:15], 0, s[2:3]
	global_store_dwordx2 v[14:15], v[16:17], off offset:768
	s_mov_b64 s[2:3], 0
